# DSA unit prologue: bias-table load no longer waits on its own round trip; first key-tile loads issued before the prologue barrier
# baseline (speedup 1.0000x reference)
; __device__ __forceinline__ void dsa_unit(int wv, const Args& A, LAS unsigned char* lds, int s, int qt) {
;     ...
;     if (tid < 16) { cnt[tid] = 0u; thr[tid] = -INFINITY; }
;     if (tid < 256) relb[tid] = A.in[9][tid];
.LBB0_919:
	s_or_b64 exec, exec, s[6:7]
	v_cmp_gt_i32_e32 vcc, s96, v82
	s_and_saveexec_b64 s[6:7], vcc
	s_cbranch_execz .LBB0_921
	v_readlane_b32 s4, v236, 12
	v_ashrrev_i32_e32 v83, 31, v82
	v_readlane_b32 s5, v236, 13
	s_nop 1
	v_lshl_add_u64 v[2:3], v[82:83], 2, s[4:5]
	global_load_dword v238, v[2:3], off
	v_lshl_add_u32 v239, v82, 2, 0
	v_add_u32_e32 v239, 0x1c880, v239

; #define DSA_LOADK(KT) do { const int kt_ = (KT); if (kt_ < ntiles) { _Pragma("unroll") for (int t_ = 0; t_ < 4; ++t_) { const h16* p_ = key_row(ws, s, (kt_ + t_) * 16 + fr, C_KI, WS_CKI, 64); \
;         nK[t_][0] = __builtin_bit_cast(h16x8, *(const u32x4*)(p_ + fq * 8)); nK[t_][1] = __builtin_bit_cast(h16x8, *(const u32x4*)(p_ + 32 + fq * 8)); } } } while (0)
; __device__ __forceinline__ void dsa_unit(int wv, const Args& A, LAS unsigned char* lds, int s, int qt) {
;     ...
;     if (tid < 256) relb[tid] = A.in[9][tid];
;     ...
;     const int ntiles = L >> 4;
;     h16x8 nK[4][2];
;     ...
; #pragma unroll
;     for (int t = 0; t < 4; ++t) { nK[t][0] = (h16x8){0, 0, 0, 0, 0, 0, 0, 0}; nK[t][1] = (h16x8){0, 0, 0, 0, 0, 0, 0, 0}; }
;     DSA_LOADK(4 * w);
.LBB0_927:
	v_cmp_gt_i32_e32 vcc, 0x100, v82
	s_and_saveexec_b64 s[6:7], vcc
	ds_write_b32 v239, v238
	s_mov_b64 exec, s[6:7]
	s_and_b32 s1, s4, 0x3fc0
	s_add_i32 s1, s1, 64
	s_lshr_b32 s81, s1, 4
	s_lshl_b32 s96, s58, 2
	s_cmp_ge_i32 s96, s81
	s_cbranch_scc1 .LBB0_929
	s_andn2_b32 s0, s0, 63
	v_or_b32_e32 v2, s0, v94
	v_ashrrev_i32_e32 v3, 31, v2
	v_lshl_add_u64 v[4:5], v[2:3], 0, s[48:49]
	v_lshlrev_b64 v[4:5], 7, v[4:5]
	v_lshl_add_u64 v[4:5], s[82:83], 0, v[4:5]
	v_lshlrev_b64 v[6:7], 1, v[66:67]
	v_lshl_add_u64 v[4:5], v[4:5], 0, v[6:7]
	global_load_dwordx4 v[58:61], v[4:5], off
	global_load_dwordx4 v[54:57], v[4:5], off offset:64
	v_or_b32_e32 v4, 16, v2
	v_ashrrev_i32_e32 v5, 31, v4
	v_lshl_add_u64 v[4:5], v[4:5], 0, s[48:49]
	v_lshlrev_b64 v[4:5], 7, v[4:5]
	v_lshl_add_u64 v[4:5], s[82:83], 0, v[4:5]
	v_lshl_add_u64 v[4:5], v[4:5], 0, v[6:7]
	global_load_dwordx4 v[62:65], v[4:5], off
	global_load_dwordx4 v[50:53], v[4:5], off offset:64
	v_or_b32_e32 v4, 32, v2
	v_or_b32_e32 v2, 48, v2
	v_ashrrev_i32_e32 v5, 31, v4
	v_ashrrev_i32_e32 v3, 31, v2
	v_lshl_add_u64 v[4:5], v[4:5], 0, s[48:49]
	v_lshl_add_u64 v[2:3], v[2:3], 0, s[48:49]
	v_lshlrev_b64 v[4:5], 7, v[4:5]
	v_lshlrev_b64 v[2:3], 7, v[2:3]
	v_lshl_add_u64 v[4:5], s[82:83], 0, v[4:5]
	v_lshl_add_u64 v[2:3], s[82:83], 0, v[2:3]
	v_lshl_add_u64 v[4:5], v[4:5], 0, v[6:7]
	v_lshl_add_u64 v[2:3], v[2:3], 0, v[6:7]
	global_load_dwordx4 v[46:49], v[4:5], off
	global_load_dwordx4 v[38:41], v[4:5], off offset:64
	global_load_dwordx4 v[42:45], v[2:3], off
	global_load_dwordx4 v[34:37], v[2:3], off offset:64
	s_branch .LBB0_930

; #define DSA_LOADK(KT) do { const int kt_ = (KT); if (kt_ < ntiles) { _Pragma("unroll") for (int t_ = 0; t_ < 4; ++t_) { const h16* p_ = key_row(ws, s, (kt_ + t_) * 16 + fr, C_KI, WS_CKI, 64); \
;         nK[t_][0] = __builtin_bit_cast(h16x8, *(const u32x4*)(p_ + fq * 8)); nK[t_][1] = __builtin_bit_cast(h16x8, *(const u32x4*)(p_ + 32 + fq * 8)); } } } while (0)
; __device__ __forceinline__ void dsa_unit(int wv, const Args& A, LAS unsigned char* lds, int s, int qt) {
;     ...
;     __syncthreads();
;     float th = -INFINITY;
;     const int ntiles = L >> 4;
;     h16x8 nK[4][2];
;     ...
; #pragma unroll
;     for (int t = 0; t < 4; ++t) { nK[t][0] = (h16x8){0, 0, 0, 0, 0, 0, 0, 0}; nK[t][1] = (h16x8){0, 0, 0, 0, 0, 0, 0, 0}; }
;     DSA_LOADK(4 * w);
;     for (int kt0 = 0; kt0 < ntiles; kt0 += 32) {
;         const int kt = kt0 + 4 * w;
;         h16x8 kc[4][2];
; #pragma unroll
;         for (int t = 0; t < 4; ++t) { kc[t][0] = nK[t][0]; kc[t][1] = nK[t][1]; }
.LBB0_930:
	s_waitcnt lgkmcnt(0)
	s_barrier
	s_lshl_b32 s94, s58, 1
	s_or_b32 s11, s94, 1
	s_mul_i32 s1, s58, 0x980
	s_lshl_b32 s12, s11, 2
	s_mulk_i32 s11, 0x4c0
	s_lshl_b32 s8, s1, 2
	s_lshl_b32 s1, s1, 1
	v_readlane_b32 s14, v236, 38
	s_lshl_b32 s13, s11, 2
	s_lshl_b32 s11, s11, 1
	v_lshlrev_b32_e32 v111, 4, v83
	s_add_i32 s0, 0, 0x1cc80
	s_add_i32 s80, s14, s1
	v_lshlrev_b32_e32 v2, 1, v83
	s_add_i32 s95, s14, s11
	v_lshlrev_b32_e32 v109, 2, v94
	s_add_i32 s59, 0, 0x1c800
	v_add_u32_e32 v112, s0, v111
	s_lshl_b32 s0, s58, 3
	s_add_i32 s67, s8, 0
	v_lshlrev_b32_e32 v95, 2, v83
	v_add_u32_e32 v107, s80, v2
	s_add_i32 s10, 0, 0x1c840
	s_add_i32 s89, s13, 0
	v_add_u32_e32 v85, s95, v2
	s_waitcnt vmcnt(7)
	v_mov_b64_e32 v[2:3], v[58:59]
	s_waitcnt vmcnt(6)
	v_mov_b64_e32 v[6:7], v[54:55]
	s_waitcnt vmcnt(5)
	v_mov_b64_e32 v[10:11], v[62:63]
	s_waitcnt vmcnt(4)
	v_mov_b64_e32 v[14:15], v[50:51]
	s_waitcnt vmcnt(3)
	v_mov_b64_e32 v[18:19], v[46:47]
	s_waitcnt vmcnt(2)
	v_mov_b64_e32 v[22:23], v[38:39]
	s_waitcnt vmcnt(1)
	v_mov_b64_e32 v[26:27], v[42:43]
	s_waitcnt vmcnt(0)
	v_mov_b64_e32 v[30:31], v[34:35]
	v_add_u32_e32 v110, s59, v109
	v_mul_u32_u24_e32 v113, 0x4c0, v94
	v_lshlrev_b32_e32 v114, 2, v88
	s_add_i32 s66, s59, s0
	v_add_u32_e32 v108, s67, v95
	v_or_b32_e32 v106, 0x100, v83
	v_or_b32_e32 v105, 0x140, v83
	v_or_b32_e32 v104, 0x180, v83
	v_or_b32_e32 v103, 0x1c0, v83
	v_or_b32_e32 v102, 0x200, v83
	v_or_b32_e32 v101, 0x240, v83
	v_or_b32_e32 v100, 0x280, v83
	v_or_b32_e32 v99, 0x2c0, v83
	v_or_b32_e32 v98, 0x300, v83
	v_or_b32_e32 v97, 0x340, v83
	v_or_b32_e32 v96, 0x380, v83
	v_or_b32_e32 v93, 0x3c0, v83
	v_or_b32_e32 v92, 0x400, v83
	v_or_b32_e32 v91, 0x440, v83
	v_or_b32_e32 v89, 0x480, v83
	s_mov_b32 s1, 0
	v_cmp_eq_u32_e64 s[8:9], 0, v83
	s_add_i32 s72, s10, s0
	s_add_i32 s59, s59, s12
	v_add_u32_e32 v90, s89, v95
	s_add_i32 s74, s10, s12
	v_add_u32_e32 v115, s10, v109
	v_or_b32_e32 v116, 0x210, v94
	v_or_b32_e32 v117, 0x220, v94
	v_or_b32_e32 v118, 0x230, v94
	v_lshl_add_u64 v[86:87], v[66:67], 1, s[82:83]
	v_mov_b32_e32 v119, 0xff800000
	v_mov_b64_e32 v[4:5], v[60:61]
	v_mov_b64_e32 v[8:9], v[56:57]
	v_mov_b64_e32 v[12:13], v[64:65]
	v_mov_b64_e32 v[16:17], v[52:53]
	v_mov_b64_e32 v[20:21], v[48:49]
	v_mov_b64_e32 v[24:25], v[40:41]
	v_mov_b64_e32 v[28:29], v[44:45]
	v_mov_b64_e32 v[32:33], v[36:37]
	s_branch .LBB0_932
